# v_transpose loop rotated so the next unit's loads are issued before the current unit's stores (no store-ack stall), plus wait-state padding in the attention epilogue
# baseline (speedup 1.0000x reference)
; #define LAS __attribute__((address_space(3)))
; #define LAS __attribute__((address_space(3)))
; DI void v_transpose(const bf16_t* z, bf16_t* VT, ldsp lds, int tid, int G, int bid) {
;     for (int u = bid; u < 2048; u += G) {
;         const int b = u >> 9, h = (u >> 7) & 3, tile = u & 127;
;         __syncthreads();
; #pragma unroll
;         for (int i = 0; i < 2; ++i) {
;             const int p = tid + 512 * i, tok = p >> 4, c16 = p & 15;
;             const u32x4 v = *(const u32x4*)(z + (size_t)(b * SEQ + tile * 64 + tok) * ZLD + C_DV + h * 128 + c16 * 8);
;             *(LAS u32x4*)(lds + tok * 272 + c16 * 16) = v;
;         }
;         __syncthreads();
;         const int e = tid & 127, tg = tid >> 7, mg = tg >> 1, h2 = tg & 1;
;         unsigned lo[8], hi[8];
; #pragma unroll
;         for (int k = 0; k < 8; ++k) {
;             lo[k] = *(LAS bf16_t*)(lds + (32 * mg + 8 * h2 + k) * 272 + e * 2);
;             hi[k] = *(LAS bf16_t*)(lds + (32 * mg + 16 + 8 * h2 + k) * 272 + e * 2);
;         }
;         u32x4* dst = (u32x4*)(VT + (size_t)((b * 4 + h) * 128 + e) * SEQ + tile * 64 + 32 * mg + 16 * h2);
;         u32x4 o0, o1;
;         o0.x = lo[0] | (lo[1] << 16); o0.y = lo[2] | (lo[3] << 16); o0.z = hi[0] | (hi[1] << 16); o0.w = hi[2] | (hi[3] << 16);
;         o1.x = lo[4] | (lo[5] << 16); o1.y = lo[6] | (lo[7] << 16); o1.z = hi[4] | (hi[5] << 16); o1.w = hi[6] | (hi[7] << 16);
;         dst[0] = o0; dst[1] = o1;
;     }
.LBB0_434:
	s_cmpk_gt_i32 s86, 0x7ff
	s_cbranch_scc1 .LBB0_437
	v_and_b32_e32 v0, 15, v136
	v_lshlrev_b32_e32 v2, 3, v0
	v_lshl_add_u32 v3, v0, 4, 0
	v_ashrrev_i32_e32 v0, 3, v136
	s_waitcnt lgkmcnt(0)
	v_bfe_u32 v5, v136, 7, 1
	v_and_b32_e32 v0, 0xffffffe0, v0
	v_lshl_or_b32 v6, v5, 3, v0
	s_movk_i32 s0, 0x110
	v_lshlrev_b32_e32 v10, 4, v5
	v_mul_lo_u32 v5, v6, s0
	v_add_u32_e32 v6, 0x200, v136
	v_and_b32_e32 v4, 0x7f, v136
	v_add_u32_e32 v11, 0, v5
	v_ashrrev_i32_e32 v5, 4, v136
	v_ashrrev_i32_e32 v6, 4, v6
	v_lshlrev_b32_e32 v9, 1, v4
	v_mul_lo_u32 v7, v5, s0
	v_mul_lo_u32 v8, v6, s0
	v_ashrrev_i32_e32 v1, 31, v0
	s_lshl_b32 s0, s86, 6
	s_lshl_b32 s1, s7, 6
	s_lshl_b32 s2, s86, 4
	s_lshl_b32 s3, s7, 4
	v_lshlrev_b32_e32 v156, 1, v2
	v_add_u32_e32 v7, v3, v7
	v_add_u32_e32 v8, v3, v8
	v_add_u32_e32 v9, v11, v9
	v_lshlrev_b32_e32 v2, 1, v10
	s_mov_b32 s6, s86
	s_mov_b32 s100, 0
	s_and_b32 s9, s2, 0xffffe000
	s_and_b32 s10, s0, 0x1fc0
	s_or_b32 s9, s9, s10
	s_and_b32 s8, s6, 0x180
	v_mov_b64_e32 v[94:95], s[70:71]
	v_add_u32_e32 v98, s9, v5
	v_add_u32_e32 v99, s9, v6
	s_lshl_b32 s30, s8, 1
	v_mad_i64_i32 v[96:97], s[8:9], v98, s97, v[94:95]
	v_mad_i64_i32 v[94:95], s[8:9], v99, s97, v[94:95]
	v_lshl_add_u64 v[96:97], v[96:97], 0, s[30:31]
	v_lshl_add_u64 v[94:95], v[94:95], 0, s[30:31]
	v_lshl_add_u64 v[96:97], v[96:97], 0, v[156:157]
	v_lshl_add_u64 v[94:95], v[94:95], 0, v[156:157]
	global_load_dwordx4 v[86:89], v[96:97], off offset:3584
	global_load_dwordx4 v[90:93], v[94:95], off offset:3584
.LBB0_436:
	s_barrier
	s_and_b32 s10, s0, 0x1fc0
	s_and_b32 s8, s6, 0xffffff80
	v_or_b32_e32 v18, s8, v4
	v_ashrrev_i32_e32 v19, 31, v18
	v_lshlrev_b64 v[18:19], 14, v[18:19]
	v_lshl_add_u64 v[18:19], s[62:63], 0, v[18:19]
	s_lshl_b32 s30, s10, 1
	v_lshl_add_u64 v[18:19], v[18:19], 0, s[30:31]
	v_mov_b32_e32 v3, v157
	v_lshl_add_u64 v[18:19], v[0:1], 1, v[18:19]
	v_lshl_add_u64 v[18:19], v[18:19], 0, v[2:3]
	s_add_i32 s6, s6, s7
	s_add_i32 s0, s0, s1
	s_add_i32 s2, s2, s3
	s_cmp_eq_u32 s100, 0
	s_cbranch_scc1 .Lvt_first
	s_waitcnt vmcnt(3)
	ds_write_b128 v7, v[86:89]
	s_waitcnt vmcnt(2)
	ds_write_b128 v8, v[90:93]
	s_branch .Lvt_w
.Lvt_first:
	s_waitcnt vmcnt(1)
	ds_write_b128 v7, v[86:89]
	s_waitcnt vmcnt(0)
	ds_write_b128 v8, v[90:93]
.Lvt_w:
	s_mov_b32 s100, 1
	s_waitcnt lgkmcnt(0)
	s_barrier
	ds_read_u16 v3, v9
	ds_read_u16 v10, v9 offset:272
	ds_read_u16 v11, v9 offset:544
	ds_read_u16 v12, v9 offset:816
	ds_read_u16 v14, v9 offset:1088
	ds_read_u16 v15, v9 offset:1360
	ds_read_u16 v16, v9 offset:1632
	ds_read_u16 v17, v9 offset:1904
	ds_read_u16 v13, v9 offset:4352
	ds_read_u16 v20, v9 offset:4624
	ds_read_u16 v21, v9 offset:4896
	ds_read_u16 v22, v9 offset:5168
	ds_read_u16 v23, v9 offset:5440
	ds_read_u16 v24, v9 offset:5712
	ds_read_u16 v25, v9 offset:5984
	ds_read_u16 v26, v9 offset:6256
	s_waitcnt lgkmcnt(14)
	v_lshl_or_b32 v10, v10, 16, v3
	s_waitcnt lgkmcnt(12)
	v_lshl_or_b32 v11, v12, 16, v11
	s_waitcnt lgkmcnt(6)
	v_lshl_or_b32 v12, v20, 16, v13
	s_waitcnt lgkmcnt(4)
	v_lshl_or_b32 v13, v22, 16, v21
	v_lshl_or_b32 v14, v15, 16, v14
	v_lshl_or_b32 v15, v17, 16, v16
	s_waitcnt lgkmcnt(2)
	v_lshl_or_b32 v16, v24, 16, v23
	s_waitcnt lgkmcnt(0)
	v_lshl_or_b32 v17, v26, 16, v25
	s_cmpk_lt_i32 s6, 0x800
	s_cbranch_scc0 .Lvt_last
	s_and_b32 s9, s2, 0xffffe000
	s_and_b32 s10, s0, 0x1fc0
	s_or_b32 s9, s9, s10
	s_and_b32 s8, s6, 0x180
	v_mov_b64_e32 v[94:95], s[70:71]
	v_add_u32_e32 v98, s9, v5
	v_add_u32_e32 v99, s9, v6
	s_lshl_b32 s30, s8, 1
	v_mad_i64_i32 v[96:97], s[8:9], v98, s97, v[94:95]
	v_mad_i64_i32 v[94:95], s[8:9], v99, s97, v[94:95]
	v_lshl_add_u64 v[96:97], v[96:97], 0, s[30:31]
	v_lshl_add_u64 v[94:95], v[94:95], 0, s[30:31]
	v_lshl_add_u64 v[96:97], v[96:97], 0, v[156:157]
	v_lshl_add_u64 v[94:95], v[94:95], 0, v[156:157]
	global_load_dwordx4 v[86:89], v[96:97], off offset:3584
	global_load_dwordx4 v[90:93], v[94:95], off offset:3584
	global_store_dwordx4 v[18:19], v[10:13], off
	global_store_dwordx4 v[18:19], v[14:17], off offset:16
	s_branch .LBB0_436
.Lvt_last:
	global_store_dwordx4 v[18:19], v[10:13], off
	global_store_dwordx4 v[18:19], v[14:17], off offset:16
